# prompt band attention loop: both V fragment read batches issued early (after QK MFMAs / before the exps) into spare registers, counted lgkmcnt before PV
# speedup vs baseline: 1.0098x; 1.0055x over previous
; #define LAS __attribute__((address_space(3)))
; __device__ __forceinline__ float x32_max(float v) { float a = v, b = v; swap32(a, b); return fmaxf(a, b); }
; #define MFMA32(a, b, c) __builtin_amdgcn_mfma_f32_32x32x16_bf16((a), (b), (c), 0, 0, 0)
; template <bool DIFF, bool FIXED, bool F32SRC> ...
;     ...
;             for (int ks = 0; ks < 2; ++ks) { a0 = MFMA32(kf0[ks], qf[ks], a0); a1 = MFMA32(kf1[ks], qf[ks], a1); }
;             __builtin_amdgcn_sched_barrier(0);
; #pragma unroll
;             for (int ks = 0; ks < 2; ++ks) { kf0[ks] = *(const LAS bf16x8*)(kb + koff[ks + 2]); kf1[ks] = *(const LAS bf16x8*)(kb + koff[ks + 2] + 32 * RB); }
;             __builtin_amdgcn_sched_barrier(0);
; #pragma unroll
;             for (int ks = 0; ks < 2; ++ks) { a0 = MFMA32(kf0[ks], qf[ks + 2], a0); a1 = MFMA32(kf1[ks], qf[ks + 2], a1); }
;             __builtin_amdgcn_sched_barrier(0);
;             bf16x8 vf[4];
;     ...
;             if (!FIXED) {
;             float mx = fmaxf(fmaxf(a0[0], a1[0]), fmaxf(a0[1], a1[1]));
; #pragma unroll
;             for (int r = 2; r < 16; r += 2) mx = fmaxf(fmaxf(mx, fmaxf(a0[r], a1[r])), fmaxf(a0[r + 1], a1[r + 1]));
;             mx = x32_max(mx);
;             if (__any(mx > 0.f)) {
;                 const float dl = fmaxf(mx, 0.f), al = __builtin_amdgcn_exp2f(-dl);
;                 lrun *= al; mrun += dl;
; #pragma unroll
;                 for (int r = 0; r < 16; ++r) { a0[r] -= dl; a1[r] -= dl; }
; #pragma unroll
;                 for (int db = 0; db < NDB; ++db)
; #pragma unroll
;                     for (int r = 0; r < 16; ++r) o[db][r] *= al;
;             }
.LBB0_343:
	v_mov_b32_e32 v51, v0
	s_waitcnt lgkmcnt(0)
	v_mfma_f32_32x32x16_bf16 v[34:49], v[94:97], v[66:69], v[34:49]
	v_add3_u32 v0, s19, v109, v106
	v_mfma_f32_32x32x16_bf16 v[50:65], v[86:89], v[66:69], v[50:65]
	v_mfma_f32_32x32x16_bf16 v[34:49], v[90:93], v[70:73], v[34:49]
	ds_read_b128 v[86:89], v0
	ds_read_b128 v[90:93], v0 offset:4096
	v_add3_u32 v0, s19, v110, v106
	ds_read_b128 v[94:97], v0
	ds_read_b128 v[116:119], v0 offset:4096
	v_mfma_f32_32x32x16_bf16 v[50:65], v[82:85], v[70:73], v[50:65]
	s_waitcnt lgkmcnt(0)
	v_mfma_f32_32x32x16_bf16 v[34:49], v[86:89], v[74:77], v[34:49]
	v_mfma_f32_32x32x16_bf16 v[50:65], v[90:93], v[74:77], v[50:65]
	v_mfma_f32_32x32x16_bf16 v[34:49], v[94:97], v[78:81], v[34:49]
	v_mfma_f32_32x32x16_bf16 v[50:65], v[116:119], v[78:81], v[50:65]
	v_add_u32_e32 v120, s19, v111
	ds_read_b64_tr_b16 v[162:163], v120 offset:8192
	ds_read_b64_tr_b16 v[164:165], v120 offset:9216
	ds_read_b64_tr_b16 v[166:167], v120 offset:10240
	ds_read_b64_tr_b16 v[168:169], v120 offset:11264
	ds_read_b64_tr_b16 v[170:171], v120 offset:12288
	ds_read_b64_tr_b16 v[172:173], v120 offset:13312
	ds_read_b64_tr_b16 v[174:175], v120 offset:14336
	ds_read_b64_tr_b16 v[176:177], v120 offset:15360
	s_nop 11
	v_max_f32_e32 v0, v51, v51
	v_max_f32_e32 v82, v35, v35
	v_max_f32_e32 v0, v82, v0
	v_max_f32_e32 v82, v52, v52
	v_max_f32_e32 v83, v36, v36
	v_max_f32_e32 v82, v83, v82
	v_max_f32_e32 v83, v53, v53
	v_max_f32_e32 v84, v37, v37
	v_max3_f32 v0, v34, v50, v0
	v_max_f32_e32 v83, v84, v83
	v_max3_f32 v0, v0, v82, v83
	v_max_f32_e32 v82, v54, v54
	v_max_f32_e32 v83, v38, v38
	v_max_f32_e32 v82, v83, v82
	v_max_f32_e32 v83, v55, v55
	v_max_f32_e32 v84, v39, v39
	v_max_f32_e32 v83, v84, v83
	v_max3_f32 v0, v0, v82, v83
	v_max_f32_e32 v82, v56, v56
	v_max_f32_e32 v83, v40, v40
	v_max_f32_e32 v82, v83, v82
	v_max_f32_e32 v83, v57, v57
	v_max_f32_e32 v84, v41, v41
	v_max_f32_e32 v83, v84, v83
	v_max3_f32 v0, v0, v82, v83
	v_max_f32_e32 v82, v58, v58
	v_max_f32_e32 v83, v42, v42
	v_max_f32_e32 v82, v83, v82
	v_max_f32_e32 v83, v59, v59
	v_max_f32_e32 v84, v43, v43
	v_max_f32_e32 v83, v84, v83
	v_max3_f32 v0, v0, v82, v83
	v_max_f32_e32 v82, v60, v60
	v_max_f32_e32 v83, v44, v44
	v_max_f32_e32 v82, v83, v82
	v_max_f32_e32 v83, v61, v61
	v_max_f32_e32 v84, v45, v45
	v_max_f32_e32 v83, v84, v83
	v_max3_f32 v0, v0, v82, v83
	v_max_f32_e32 v82, v62, v62
	v_max_f32_e32 v83, v46, v46
	v_max_f32_e32 v82, v83, v82
	v_max_f32_e32 v83, v63, v63
	v_max_f32_e32 v84, v47, v47
	v_max_f32_e32 v83, v84, v83
	v_max3_f32 v0, v0, v82, v83
	v_max_f32_e32 v82, v64, v64
	v_max_f32_e32 v83, v48, v48
	v_max_f32_e32 v82, v83, v82
	v_max_f32_e32 v83, v65, v65
	v_max_f32_e32 v84, v49, v49
	v_max_f32_e32 v83, v84, v83
	v_max3_f32 v0, v0, v82, v83
	v_mov_b32_e32 v82, v0
	s_nop 1
	v_permlane32_swap_b32 v0, v82
	s_nop 1
	s_nop 0
	v_max_f32_e32 v82, v82, v82
	v_max_f32_e32 v0, v0, v0
	v_max_f32_e32 v0, v0, v82
	v_cmp_lt_f32_e32 vcc, 0, v0
	s_cbranch_vccz .LBB0_345
	v_max_f32_e32 v0, v0, v0
	v_max_f32_e32 v0, 0, v0
	v_exp_f32_e64 v82, -v0
	v_pk_add_f32 v[34:35], v[34:35], v[0:1] op_sel_hi:[1,0] neg_lo:[0,1] neg_hi:[0,1]
	v_pk_add_f32 v[50:51], v[50:51], v[0:1] op_sel_hi:[1,0] neg_lo:[0,1] neg_hi:[0,1]
	v_pk_add_f32 v[36:37], v[36:37], v[0:1] op_sel_hi:[1,0] neg_lo:[0,1] neg_hi:[0,1]
	v_mul_f32_e32 v112, v112, v82
	v_pk_add_f32 v[52:53], v[52:53], v[0:1] op_sel_hi:[1,0] neg_lo:[0,1] neg_hi:[0,1]
	v_pk_add_f32 v[38:39], v[38:39], v[0:1] op_sel_hi:[1,0] neg_lo:[0,1] neg_hi:[0,1]
	v_pk_add_f32 v[54:55], v[54:55], v[0:1] op_sel_hi:[1,0] neg_lo:[0,1] neg_hi:[0,1]
	v_pk_add_f32 v[40:41], v[40:41], v[0:1] op_sel_hi:[1,0] neg_lo:[0,1] neg_hi:[0,1]
	v_pk_add_f32 v[56:57], v[56:57], v[0:1] op_sel_hi:[1,0] neg_lo:[0,1] neg_hi:[0,1]
	v_pk_add_f32 v[42:43], v[42:43], v[0:1] op_sel_hi:[1,0] neg_lo:[0,1] neg_hi:[0,1]
	v_pk_add_f32 v[58:59], v[58:59], v[0:1] op_sel_hi:[1,0] neg_lo:[0,1] neg_hi:[0,1]
	v_pk_add_f32 v[44:45], v[44:45], v[0:1] op_sel_hi:[1,0] neg_lo:[0,1] neg_hi:[0,1]
	v_pk_add_f32 v[60:61], v[60:61], v[0:1] op_sel_hi:[1,0] neg_lo:[0,1] neg_hi:[0,1]
	v_pk_add_f32 v[46:47], v[46:47], v[0:1] op_sel_hi:[1,0] neg_lo:[0,1] neg_hi:[0,1]
	v_pk_add_f32 v[62:63], v[62:63], v[0:1] op_sel_hi:[1,0] neg_lo:[0,1] neg_hi:[0,1]
	v_pk_add_f32 v[48:49], v[48:49], v[0:1] op_sel_hi:[1,0] neg_lo:[0,1] neg_hi:[0,1]
	v_pk_add_f32 v[64:65], v[64:65], v[0:1] op_sel_hi:[1,0] neg_lo:[0,1] neg_hi:[0,1]
	v_pk_mul_f32 v[16:17], v[16:17], v[82:83] op_sel_hi:[1,0]
	v_pk_mul_f32 v[14:15], v[14:15], v[82:83] op_sel_hi:[1,0]
	v_pk_mul_f32 v[12:13], v[12:13], v[82:83] op_sel_hi:[1,0]
	v_pk_mul_f32 v[10:11], v[10:11], v[82:83] op_sel_hi:[1,0]
	v_pk_mul_f32 v[8:9], v[8:9], v[82:83] op_sel_hi:[1,0]
	v_pk_mul_f32 v[6:7], v[6:7], v[82:83] op_sel_hi:[1,0]
	v_pk_mul_f32 v[4:5], v[4:5], v[82:83] op_sel_hi:[1,0]
	v_pk_mul_f32 v[2:3], v[2:3], v[82:83] op_sel_hi:[1,0]
	v_pk_mul_f32 v[32:33], v[32:33], v[82:83] op_sel_hi:[1,0]
	v_pk_mul_f32 v[30:31], v[30:31], v[82:83] op_sel_hi:[1,0]
	v_pk_mul_f32 v[28:29], v[28:29], v[82:83] op_sel_hi:[1,0]
	v_pk_mul_f32 v[26:27], v[26:27], v[82:83] op_sel_hi:[1,0]
	v_pk_mul_f32 v[24:25], v[24:25], v[82:83] op_sel_hi:[1,0]
	v_pk_mul_f32 v[22:23], v[22:23], v[82:83] op_sel_hi:[1,0]
	v_pk_mul_f32 v[20:21], v[20:21], v[82:83] op_sel_hi:[1,0]
	v_pk_mul_f32 v[18:19], v[18:19], v[82:83] op_sel_hi:[1,0]
	v_add_f32_e32 v114, v114, v0
; __device__ __forceinline__ unsigned cvt_pk_bf16(float lo, float hi) { unsigned r; asm volatile("v_cvt_pk_bf16_f32 %0, %1, %2" : "=v"(r) : "v"(lo), "v"(hi)); return r; }
; #define MFMA32(a, b, c) __builtin_amdgcn_mfma_f32_32x32x16_bf16((a), (b), (c), 0, 0, 0)
; #define ATT_VLOAD(dst, db) do { _Pragma("unroll") for (int ks = 0; ks < 4; ++ks) { \
;                 const s16x4 lo_ = vtr(vb + (2 * ks) * (NDB * 512) + (db) * 512 + vlane), h4_ = vtr(vb + (2 * ks + 1) * (NDB * 512) + (db) * 512 + vlane); \
;                 dst[ks] = (bf16x8){lo_[0], lo_[1], lo_[2], lo_[3], h4_[0], h4_[1], h4_[2], h4_[3]}; } } while (0)
; template <bool DIFF, bool FIXED, bool F32SRC> ...
;     ...
;             float ls = 0.f;
; #pragma unroll
;             for (int r = 0; r < 16; ++r) { a0[r] = __builtin_amdgcn_exp2f(a0[r]); a1[r] = __builtin_amdgcn_exp2f(a1[r]); ls += a0[r] + a1[r]; }
;             lrun += ls;
;             bf16x8 pf[4];
; #pragma unroll
;             for (int ks = 0; ks < 4; ++ks) { u32x4 p;
; #pragma unroll
;                 for (int e = 0; e < 4; ++e) p[e] = (ks < 2) ? cvt_pk_bf16(a0[8 * ks + 2 * e], a0[8 * ks + 2 * e + 1]) : cvt_pk_bf16(a1[8 * (ks - 2) + 2 * e], a1[8 * (ks - 2) + 2 * e + 1]);
;                 pf[ks] = __builtin_bit_cast(bf16x8, p); }
; #pragma unroll
;             for (int db = 0; db < NDB; ++db) {
;                 ATT_VLOAD(vf, db);
;                 __builtin_amdgcn_sched_barrier(0);
; #pragma unroll
;                 for (int ks = 0; ks < 4; ++ks) o[db] = MFMA32(vf[ks], pf[ks], o[db]);
;                 __builtin_amdgcn_sched_barrier(0);
;             }
.LBB0_345:
	s_waitcnt lgkmcnt(7)
	ds_read_b64_tr_b16 v[178:179], v120 offset:8704
	ds_read_b64_tr_b16 v[180:181], v120 offset:9728
	ds_read_b64_tr_b16 v[182:183], v120 offset:10752
	ds_read_b64_tr_b16 v[184:185], v120 offset:11776
	ds_read_b64_tr_b16 v[186:187], v120 offset:12800
	ds_read_b64_tr_b16 v[188:189], v120 offset:13824
	ds_read_b64_tr_b16 v[190:191], v120 offset:14848
	ds_read_b64_tr_b16 v[192:193], v120 offset:15872
	v_exp_f32_e32 v86, v34
	v_exp_f32_e32 v87, v50
	v_exp_f32_e32 v0, v35
	v_exp_f32_e32 v82, v51
	v_exp_f32_e32 v88, v52
	v_add_f32_e32 v83, v87, v86
	v_exp_f32_e32 v84, v53
	v_pk_add_f32 v[34:35], v[82:83], v[0:1]
	v_exp_f32_e32 v83, v36
	v_pk_add_f32 v[50:51], v[34:35], v[34:35] op_sel_hi:[0,1]
	v_exp_f32_e32 v50, v37
	v_exp_f32_e32 v52, v55
	v_add_f32_e32 v85, v88, v83
	v_pk_add_f32 v[34:35], v[84:85], v[50:51]
	s_nop 0
	v_pk_add_f32 v[36:37], v[34:35], v[34:35] op_sel_hi:[0,1]
	v_exp_f32_e32 v51, v38
	v_exp_f32_e32 v85, v54
	v_exp_f32_e32 v36, v39
	v_exp_f32_e32 v54, v57
	v_add_f32_e32 v53, v85, v51
	v_pk_add_f32 v[34:35], v[52:53], v[36:37]
	v_exp_f32_e32 v37, v40
	v_pk_add_f32 v[38:39], v[34:35], v[34:35] op_sel_hi:[0,1]
	v_exp_f32_e32 v53, v56
	v_exp_f32_e32 v38, v41
	v_exp_f32_e32 v56, v59
	v_add_f32_e32 v55, v53, v37
	v_pk_add_f32 v[34:35], v[54:55], v[38:39]
	v_exp_f32_e32 v39, v42
	v_pk_add_f32 v[40:41], v[34:35], v[34:35] op_sel_hi:[0,1]
	v_exp_f32_e32 v55, v58
	v_exp_f32_e32 v40, v43
	v_exp_f32_e32 v58, v61
	v_add_f32_e32 v57, v55, v39
	v_pk_add_f32 v[34:35], v[56:57], v[40:41]
	v_exp_f32_e32 v41, v44
	v_pk_add_f32 v[42:43], v[34:35], v[34:35] op_sel_hi:[0,1]
	v_exp_f32_e32 v57, v60
	v_exp_f32_e32 v42, v45
	v_exp_f32_e32 v60, v63
	v_add_f32_e32 v59, v57, v41
	v_pk_add_f32 v[34:35], v[58:59], v[42:43]
	v_exp_f32_e32 v43, v46
	v_pk_add_f32 v[44:45], v[34:35], v[34:35] op_sel_hi:[0,1]
	v_exp_f32_e32 v59, v62
	v_exp_f32_e32 v44, v47
	v_exp_f32_e32 v62, v65
	v_add_f32_e32 v61, v59, v43
	v_pk_add_f32 v[34:35], v[60:61], v[44:45]
	v_exp_f32_e32 v45, v48
	v_pk_add_f32 v[46:47], v[34:35], v[34:35] op_sel_hi:[0,1]
	v_exp_f32_e32 v61, v64
	v_exp_f32_e32 v46, v49
	v_add_f32_e32 v63, v61, v45
	v_pk_add_f32 v[34:35], v[62:63], v[46:47]
	s_nop 0
	v_add_f32_e32 v89, v34, v35
	v_cvt_pk_bf16_f32 v34, v86, v0
	v_add_u32_e32 v0, s19, v111
	v_cvt_pk_bf16_f32 v35, v83, v50
	v_cvt_pk_bf16_f32 v36, v51, v36
	v_cvt_pk_bf16_f32 v37, v37, v38
	v_cvt_pk_bf16_f32 v38, v39, v40
	v_cvt_pk_bf16_f32 v39, v41, v42
	v_cvt_pk_bf16_f32 v40, v43, v44
	v_cvt_pk_bf16_f32 v41, v45, v46
	v_cvt_pk_bf16_f32 v42, v87, v82
	v_cvt_pk_bf16_f32 v43, v88, v84
	v_cvt_pk_bf16_f32 v44, v85, v52
	v_cvt_pk_bf16_f32 v45, v53, v54
	v_cvt_pk_bf16_f32 v46, v55, v56
	v_cvt_pk_bf16_f32 v47, v57, v58
	v_cvt_pk_bf16_f32 v48, v59, v60
	v_cvt_pk_bf16_f32 v49, v61, v62
	s_waitcnt lgkmcnt(8)
	v_mfma_f32_32x32x16_bf16 v[18:33], v[162:165], v[34:37], v[18:33]
	v_mfma_f32_32x32x16_bf16 v[18:33], v[166:169], v[38:41], v[18:33]
	v_mfma_f32_32x32x16_bf16 v[18:33], v[170:173], v[42:45], v[18:33]
	v_mfma_f32_32x32x16_bf16 v[18:33], v[174:177], v[46:49], v[18:33]
	s_waitcnt lgkmcnt(0)
	v_mfma_f32_32x32x16_bf16 v[2:17], v[178:181], v[34:37], v[2:17]
	v_mfma_f32_32x32x16_bf16 v[2:17], v[182:185], v[38:41], v[2:17]
	v_mfma_f32_32x32x16_bf16 v[2:17], v[186:189], v[42:45], v[2:17]
	v_mfma_f32_32x32x16_bf16 v[2:17], v[190:193], v[46:49], v[2:17]
	v_add_f32_e32 v112, v112, v89
	s_andn2_b64 vcc, exec, s[12:13]
	s_mov_b64 s[12:13], -1
	s_cbranch_vccnz .LBB0_335
